# out-proj sample-panel tiles deferred past grid barrier 4 (run by 4 XCD-7 workgroups with spare FFN-in slot): out-proj is exactly 4 full rounds; y-sample f32 copy moved to FFN-out start
# speedup vs baseline: 1.0116x; 1.0116x over previous
.LBB0_496:
	s_or_b64 exec, exec, s[0:1]
	s_waitcnt lgkmcnt(0)
	s_barrier
	s_mov_b32 s99, 0
	s_mov_b32 s100, s2
	s_movk_i32 s101, 0x400
.Lp3_entry:
	v_mov_b32_e32 v10, v0
	s_cmp_lt_i32 s100, s101
	s_cselect_b64 s[0:1], -1, 0
	s_cmp_ge_i32 s100, s101
	v_readfirstlane_b32 s6, v10
	s_cbranch_scc1 .LBB0_502
	s_and_b32 s7, s100, 7
	s_lshl_b32 s8, s7, 7
	s_ashr_i32 s3, s100, 3
	s_add_i32 s3, s8, s3
	s_cmpk_lt_i32 s100, 0x400
	s_cselect_b32 s3, s3, s100
	s_ashr_i32 s4, s3, 31
	s_lshr_b32 s4, s4, 28
	s_add_i32 s4, s3, s4
	s_ashr_i32 s4, s4, 4
	s_lshl_b32 s7, s4, 2
	s_sub_i32 s5, 0x101, s7
	s_lshl_b32 s4, s4, 4
	s_min_u32 s8, s5, 4
	s_sub_i32 s3, s3, s4
	s_sext_i32_i8 s4, s3
	v_cvt_f32_ubyte0_e32 v2, s8
	v_cvt_f32_i32_e32 v1, s4
	v_rcp_iflag_f32_e32 v3, v2
	s_ashr_i32 s4, s4, 30
	s_or_b32 s9, s4, 1
	v_mul_f32_e32 v3, v1, v3
	v_trunc_f32_e32 v3, v3
	v_fma_f32 v1, -v3, v2, v1
	v_cvt_i32_f32_e32 v3, v3
	v_cmp_ge_f32_e64 s[4:5], |v1|, v2
	s_and_b64 s[4:5], s[4:5], exec
	s_cselect_b32 s4, s9, 0
	v_readfirstlane_b32 s5, v3
	s_add_i32 s4, s5, s4
	s_sext_i32_i8 s26, s4
	s_mul_i32 s4, s4, s8
	s_sub_i32 s3, s3, s4
	s_sext_i32_i8 s3, s3
	s_add_i32 s28, s7, s3

.LBB0_505:
	s_add_u32 s8, s80, 0xc3000
	s_addc_u32 s9, s81, 0
	s_add_u32 s12, s80, 0x103800
	s_addc_u32 s13, s81, 0
	s_lshl_b32 s5, s5, 5
	s_mov_b64 s[14:15], 0x80
	s_and_b32 s18, s5, 0x60
	s_add_i32 m0, s29, 0x18000
	v_lshl_add_u64 v[8:9], v[8:9], 0, s[14:15]
	s_lshl_b32 s7, s4, 13
	s_lshl_b32 s5, s18, 7
	s_waitcnt vmcnt(2)
	s_barrier
	global_load_lds_dwordx4 v[8:9], off
	v_lshl_add_u64 v[6:7], v[6:7], 0, s[14:15]
	s_add_i32 m0, s29, 0x1a000
	s_add_i32 s52, s29, 0x8000
	s_add_i32 s53, s29, 0xa000
	global_load_lds_dwordx4 v[6:7], off
	v_lshl_add_u64 v[2:3], v[2:3], 0, s[14:15]
	s_mov_b32 m0, s52
	s_add_u32 s16, s38, 0x40080
	global_load_lds_dwordx4 v[2:3], off
	v_lshl_add_u64 v[2:3], v[4:5], 0, s[14:15]
	s_mov_b32 m0, s53
	s_addc_u32 s17, s39, 0
	global_load_lds_dwordx4 v[2:3], off
	s_add_i32 m0, s29, 0x1c000
	v_lshl_add_u64 v[2:3], s[16:17], 0, v[174:175]
	global_load_lds_dwordx4 v[2:3], off
	v_lshl_add_u64 v[2:3], s[16:17], 0, v[178:179]
	s_add_i32 m0, s29, 0x1e000
	s_cmpk_lt_u32 s6, 0x100
	global_load_lds_dwordx4 v[2:3], off
	v_bfe_u32 v3, v10, 4, 2
	v_and_b32_e32 v2, 15, v10
	v_lshlrev_b32_e32 v4, 4, v3
	v_lshl_or_b32 v1, s4, 6, v2
	v_lshl_or_b32 v2, v2, 6, v4
	v_lshlrev_b32_e32 v4, 2, v10
	v_and_b32_e32 v4, 32, v4
	v_bitop3_b32 v5, v2, s7, v4 bitop3:0xde
	v_bitop3_b32 v171, v2, s5, v4 bitop3:0xde
	v_lshlrev_b32_e32 v2, 14, v11
	v_and_b32_e32 v2, 0xffff8000, v2
	v_cmp_eq_u32_e64 s[4:5], 0, v3
	v_lshl_or_b32 v189, v3, 3, s18
	v_lshl_add_u32 v2, v12, 11, v2
	v_and_b32_e32 v3, 1, v11
	v_lshl_or_b32 v2, v3, 6, v2
	v_lshl_add_u32 v180, v13, 1, v2
	v_lshlrev_b32_e32 v2, 14, v14
	v_and_b32_e32 v2, 0xffff8000, v2
	s_waitcnt vmcnt(0)
	v_lshl_add_u32 v2, v15, 11, v2
	v_and_b32_e32 v3, 1, v14
	s_cselect_b64 s[16:17], -1, 0
	v_lshl_or_b32 v2, v3, 6, v2
	s_add_i32 s55, 0, 0x10000
	s_add_i32 s56, 0, 0x14000
	v_mov_b32_e32 v181, v175
	v_lshl_add_u32 v182, v16, 1, v2
	v_mov_b32_e32 v183, v175
	v_mov_b32_e32 v184, s101
	v_mov_b32_e32 v185, 0
	v_add_u32_e32 v186, -1, v184
	v_mov_b32_e32 v187, 0
	v_add_u32_e32 v193, s55, v171
	v_add_u32_e32 v195, s56, v171
	v_add_u32_e32 v197, 0, v5
	s_barrier
	s_branch .LBB0_508

.LBB0_508:
	s_add_i32 s51, s51, 1
	s_mul_i32 s6, s51, s90
	s_mul_hi_u32 s7, s51, s82
	s_add_i32 s7, s7, s6
	s_mul_i32 s6, s51, s82
	s_add_u32 s22, s6, s100
	s_addc_u32 s23, s7, s86
	v_cmp_gt_i64_e32 vcc, s[22:23], v[186:187]
	v_cmp_lt_i64_e64 s[6:7], s[22:23], v[184:185]
	s_cbranch_vccnz .LBB0_514
	s_ashr_i32 s18, s22, 31
	s_lshr_b32 s18, s18, 29
	s_add_i32 s20, s22, s18
	s_and_b32 s18, s20, -8
	s_sub_i32 s21, s22, s18
	s_lshl_b32 s22, s21, 7
	s_ashr_i32 s18, s20, 3
	s_add_i32 s18, s22, s18
	s_ashr_i32 s19, s18, 31
	s_lshr_b32 s19, s19, 28
	s_add_i32 s19, s18, s19
	s_ashr_i32 s20, s19, 4
	s_lshl_b32 s20, s20, 2
	s_sub_i32 s21, 0x101, s20
	s_min_i32 s21, s21, 4
	s_abs_i32 s22, s21
	v_cvt_f32_u32_e32 v2, s22
	s_sub_i32 s24, 0, s22
	s_and_b32 s19, s19, -16
	s_sub_i32 s19, s18, s19
	v_rcp_iflag_f32_e32 v2, v2
	s_abs_i32 s18, s19
	s_xor_b32 s23, s19, s21
	s_ashr_i32 s23, s23, 31
	v_mul_f32_e32 v2, 0x4f7ffffe, v2
	v_cvt_u32_f32_e32 v2, v2
	s_nop 0
	v_readfirstlane_b32 s25, v2
	s_mul_i32 s24, s24, s25
	s_mul_hi_u32 s24, s25, s24
	s_add_i32 s25, s25, s24
	s_mul_hi_u32 s24, s18, s25
	s_mul_i32 s25, s24, s22
	s_sub_i32 s18, s18, s25
	s_add_i32 s27, s24, 1
	s_sub_i32 s25, s18, s22
	s_cmp_ge_u32 s18, s22
	s_cselect_b32 s24, s27, s24
	s_cselect_b32 s18, s25, s18
	s_add_i32 s25, s24, 1
	s_cmp_ge_u32 s18, s22
	s_cselect_b32 s18, s25, s24
	s_xor_b32 s18, s18, s23
	s_sub_i32 s18, s18, s23
	s_mul_i32 s21, s18, s21
	s_sub_i32 s19, s19, s21
	s_add_i32 s20, s20, s19

.LBB0_538:
	s_waitcnt vmcnt(0)
	s_waitcnt lgkmcnt(0)
	s_barrier
	s_cmp_lg_u32 s99, 0
	s_cbranch_scc1 .Lp4_entry
	s_and_saveexec_b64 s[0:1], s[96:97]
	s_cbranch_execz .LBB0_590
	s_add_i32 s3, 0, 0x23fe0
	v_mov_b32_e32 v1, s3
	s_waitcnt vmcnt(0) expcnt(0) lgkmcnt(0)
	ds_read_b32 v3, v1
	s_add_i32 s3, 0, 0x23fe4
	v_mov_b32_e32 v1, s3
	ds_read_b32 v1, v1
	s_waitcnt lgkmcnt(1)
	v_cmp_ne_u32_e32 vcc, 0, v3
	s_cbranch_vccnz .LBB0_554
	s_add_u32 s4, s80, 0x104a00
	s_addc_u32 s5, s81, 0
	s_add_u32 s6, s80, 0x104c00
	s_addc_u32 s7, s81, 0
	s_add_u32 s8, s80, 0x104d00
	s_addc_u32 s9, s81, 0
	s_add_u32 s12, s80, 0x104e00
	s_addc_u32 s13, s81, 0
	s_add_u32 s14, s80, 0x104f00
	s_addc_u32 s15, s81, 0
	s_add_u32 s16, s80, 0x105000
	s_addc_u32 s17, s81, 0
	s_add_u32 s18, s80, 0x105100
	s_addc_u32 s19, s81, 0
	s_add_u32 s20, s80, 0x105200
	s_addc_u32 s21, s81, 0
	s_add_u32 s22, s80, 0x105300
	s_addc_u32 s23, s81, 0
	s_add_u32 s24, s80, 0x105400
	s_addc_u32 s25, s81, 0
	s_add_u32 s26, s80, 0x105500
	s_addc_u32 s27, s81, 0
	s_add_u32 s28, s80, 0x105600
	s_addc_u32 s29, s81, 0
	s_add_u32 s30, s80, 0x105700
	s_addc_u32 s31, s81, 0
	s_add_u32 s38, s80, 0x105800
	s_addc_u32 s39, s81, 0
	s_add_u32 s44, s80, 0x105900
	s_addc_u32 s45, s81, 0
	s_add_u32 s46, s80, 0x105a00
	s_addc_u32 s47, s81, 0
	s_mul_i32 s3, s83, s93
	s_add_u32 s48, s80, 0x105b00
	s_mul_i32 s3, s3, s82
	s_addc_u32 s49, s81, 0
	s_mov_b32 s33, 1
	v_mov_b32_e32 v17, 0
	s_branch .LBB0_542

.LBB0_590:
	s_or_b64 exec, exec, s[0:1]
	s_waitcnt lgkmcnt(0)
	s_barrier
	s_and_b32 s3, s2, 0xe7
	s_cmpk_lg_u32 s3, 0xe7
	s_cbranch_scc1 .Lp4_entry
	s_mov_b32 s99, 1
	s_bfe_u32 s100, s2, 0x20003
	s_addk_i32 s100, 0x400
	s_movk_i32 s101, 0x404
	s_branch .Lp3_entry
.Lp4_entry:
	s_add_u32 s8, s80, 0x9a08800
	s_addc_u32 s9, s81, 0
	v_mov_b32_e32 v11, v0
	s_cmpk_lt_i32 s2, 0x1616
	s_nop 0
	v_readfirstlane_b32 s5, v11
	s_cbranch_scc0 .LBB0_613
	v_lshlrev_b32_e32 v1, 4, v11
	v_add_u32_e32 v2, 0x2000, v1
	v_ashrrev_i32_e32 v3, 31, v2
	v_lshrrev_b32_e32 v3, 22, v3
	v_add_u32_e32 v3, v2, v3
	v_ashrrev_i32_e32 v10, 10, v3
	v_mul_i32_i24_e32 v3, 0x400, v10
	v_sub_u32_e32 v2, v2, v3
	v_lshrrev_b32_e32 v3, 4, v2
	v_bitop3_b32 v2, v3, v2, 32 bitop3:0x6c
	v_ashrrev_i32_e32 v3, 31, v2
	v_lshrrev_b32_e32 v3, 26, v3
	v_add_u32_e32 v3, v2, v3
	v_lshlrev_b32_e32 v4, 3, v10
	v_ashrrev_i32_e32 v12, 6, v3
	v_and_b32_e32 v4, -16, v4
	v_add_u32_e32 v4, v12, v4
	v_and_b32_e32 v5, 3, v12
	s_mov_b32 s0, 0x1fffe0
	v_lshrrev_b32_e32 v6, 2, v4
	v_lshlrev_b32_e32 v7, 1, v4
	v_and_b32_e32 v3, 0xc0, v3
	v_and_or_b32 v5, v4, s0, v5
	v_and_b32_e32 v6, 4, v6
	v_and_b32_e32 v7, 24, v7
	v_sub_u32_e32 v2, v2, v3
	v_mov_b32_e32 v3, 1
	v_or3_b32 v5, v5, v6, v7
	v_lshlrev_b32_e32 v6, 5, v10
	v_ashrrev_i16_sdwa v2, v3, sext(v2) dst_sel:DWORD dst_unused:UNUSED_PAD src0_sel:DWORD src1_sel:BYTE_0
	v_and_b32_e32 v6, 32, v6
	v_bfe_i32 v13, v2, 0, 16
	v_add_lshl_u32 v2, v6, v13, 1
	v_lshl_add_u32 v130, v5, 11, v2
	s_waitcnt vmcnt(8)
	v_lshl_add_u32 v132, v4, 11, v2
	v_bfe_i32 v2, v11, 27, 1
	v_lshrrev_b32_e32 v2, 22, v2
	v_add_u32_e32 v2, v1, v2
	v_and_b32_e32 v2, 0xfffffc00, v2
	v_sub_u32_e32 v1, v1, v2
	v_lshrrev_b32_e32 v2, 4, v1
	v_ashrrev_i32_e32 v4, 31, v11
	v_bitop3_b32 v1, v2, v1, 32 bitop3:0x6c
	v_lshrrev_b32_e32 v4, 26, v4
	v_ashrrev_i32_e32 v2, 31, v1
	v_add_u32_e32 v4, v11, v4
	v_lshrrev_b32_e32 v2, 26, v2
	v_ashrrev_i32_e32 v15, 6, v4
	v_add_u32_e32 v2, v1, v2
	v_lshlrev_b32_e32 v4, 3, v15
	v_ashrrev_i32_e32 v14, 6, v2
	v_and_b32_e32 v4, -16, v4
	s_add_u32 s3, s80, 0x888800
	v_add_u32_e32 v4, v14, v4
	v_and_b32_e32 v5, 3, v14
	s_addc_u32 s17, s81, 0
	v_and_or_b32 v5, v4, s0, v5
	s_lshr_b32 s0, s86, 29
	s_add_i32 s0, s2, s0
	s_ashr_i32 s1, s0, 3
	s_and_b32 s0, s0, -8
	s_sub_i32 s0, s2, s0
	s_ashr_i32 s12, s5, 6
	s_mul_i32 s6, s0, 0x2c2
	s_ashr_i32 s14, s5, 8
	s_lshl_b32 s19, s12, 10
	s_add_i32 s6, s6, 6
	s_mul_i32 s4, s0, 0x2c3
	s_cmp_lt_i32 s0, 6
	s_cselect_b32 s0, s4, s6
	s_add_i32 s0, s0, s1
	s_mul_hi_i32 s1, s0, 0x2e8ba2e9
	s_lshr_b32 s4, s1, 31
	s_ashr_i32 s1, s1, 4
	v_lshrrev_b32_e32 v6, 2, v4
	v_lshlrev_b32_e32 v7, 1, v4
	v_and_b32_e32 v2, 0xc0, v2
	s_add_i32 s1, s1, s4
	v_and_b32_e32 v6, 4, v6
	v_and_b32_e32 v7, 24, v7
	v_sub_u32_e32 v1, v1, v2
	s_lshl_b32 s6, s1, 2
	v_or3_b32 v5, v5, v6, v7
	v_lshlrev_b32_e32 v6, 5, v15
	v_ashrrev_i16_sdwa v1, v3, sext(v1) dst_sel:DWORD dst_unused:UNUSED_PAD src0_sel:DWORD src1_sel:BYTE_0
	s_sub_i32 s4, 0x101, s6
	v_and_b32_e32 v6, 32, v6
	v_bfe_i32 v16, v1, 0, 16
	s_min_u32 s7, s4, 4
	s_mulk_i32 s1, 0x58
	v_add_lshl_u32 v1, v6, v16, 1
	s_sub_i32 s13, s0, s1
	v_cvt_f32_ubyte0_e32 v3, s7
	v_lshl_add_u32 v134, v5, 11, v1
	v_cvt_f32_i32_e32 v2, s13
	v_rcp_iflag_f32_e32 v5, v3
	v_lshl_add_u32 v136, v4, 11, v1
	s_ashr_i32 s0, s13, 30
	s_or_b32 s4, s0, 1
	v_mul_f32_e32 v1, v2, v5
	v_trunc_f32_e32 v1, v1
	v_fma_f32 v2, -v1, v3, v2
	v_cvt_i32_f32_e32 v1, v1
	v_cmp_ge_f32_e64 s[0:1], |v2|, v3
	s_and_b64 s[0:1], s[0:1], exec
	s_cselect_b32 s0, s4, 0
	v_readfirstlane_b32 s1, v1
	s_add_i32 s4, s1, s0
	s_mul_i32 s0, s4, s7
	s_sub_i32 s0, s13, s0
	s_sext_i32_i8 s0, s0
	s_add_i32 s0, s6, s0
	s_ashr_i32 s1, s0, 31
	s_bfe_i64 s[20:21], s[4:5], 0x80000
	s_lshl_b64 s[6:7], s[0:1], 19
	s_lshl_b64 s[20:21], s[20:21], 19
	s_add_u32 s30, s3, s20
	s_addc_u32 s31, s17, s21
	s_add_i32 s44, s19, 0
	s_add_i32 m0, s44, 0x10000
	v_mov_b32_e32 v135, 0
	global_load_lds_dwordx4 v134, s[30:31]
	s_add_i32 m0, s44, 0x12000
	s_add_u32 s20, s30, 0x40000
	global_load_lds_dwordx4 v130, s[30:31]
	s_addc_u32 s21, s31, 0
	s_add_i32 m0, s44, 0x14000
	v_mov_b32_e32 v131, v135
	global_load_lds_dwordx4 v134, s[20:21]
	s_add_i32 m0, s44, 0x16000
	s_add_u32 s28, s40, s6
	s_addc_u32 s29, s41, s7
	s_add_i32 s45, s44, 0x2000
	global_load_lds_dwordx4 v130, s[20:21]
	s_mov_b32 m0, s44
	s_add_u32 s6, s28, 0x40000
	global_load_lds_dwordx4 v136, s[28:29]
	s_mov_b32 m0, s45
	s_addc_u32 s7, s29, 0
	s_add_i32 s33, s44, 0x4000
	global_load_lds_dwordx4 v132, s[28:29]
	s_mov_b32 m0, s33
	s_add_i32 s46, s44, 0x6000
	global_load_lds_dwordx4 v136, s[6:7]
	s_mov_b32 m0, s46
	v_mov_b32_e32 v137, v135
	global_load_lds_dwordx4 v132, s[6:7]
	v_mov_b32_e32 v133, v135
	s_cmp_eq_u32 s14, 1
	s_mov_b32 s47, 0
	v_lshl_add_u64 v[8:9], s[30:31], 0, v[134:135]
	v_lshl_add_u64 v[6:7], s[30:31], 0, v[130:131]
	v_lshl_add_u64 v[2:3], s[28:29], 0, v[136:137]
	s_cselect_b64 s[6:7], -1, 0
	s_cmp_lg_u32 s14, 1
	v_lshl_add_u64 v[4:5], s[28:29], 0, v[132:133]
	s_cbranch_scc1 .LBB0_596
	s_barrier

.LBB0_666:
	s_or_b64 exec, exec, s[0:1]
	s_waitcnt lgkmcnt(0)
	v_mov_b32_e32 v1, v0
	s_barrier
	v_readlane_b32 s36, v252, 20
	v_mov_b32_e32 v1, v0
	v_readlane_b32 s0, v252, 17
	s_nop 1
	v_add_u32_e32 v2, s0, v1
	s_mov_b32 s0, 0x8000
	v_cmp_gt_i32_e32 vcc, s0, v2
	s_and_saveexec_b64 s[0:1], vcc
	s_cbranch_execz .LBB0_593
	v_ashrrev_i32_e32 v3, 31, v2
	v_lshlrev_b64 v[6:7], 5, v[2:3]
	v_lshl_add_u64 v[4:5], v[2:3], 4, s[80:81]
	s_mov_b64 s[4:5], 0x9908800
	s_ashr_i32 s37, s36, 31
	v_lshl_add_u64 v[6:7], s[78:79], 0, v[6:7]
	s_mov_b64 s[6:7], 0x10000000
	v_lshl_add_u64 v[4:5], v[4:5], 0, s[4:5]
	s_lshl_b64 s[4:5], s[36:37], 4
	v_lshl_add_u64 v[6:7], v[6:7], 0, s[6:7]
	s_lshl_b64 s[6:7], s[36:37], 5
	s_mov_b64 s[100:101], 0
	s_movk_i32 s3, 0x7fff
.LBB0_592:
	global_load_dwordx4 v[8:11], v[4:5], off
	v_add_u32_e32 v2, s36, v2
	v_cmp_lt_i32_e32 vcc, s3, v2
	v_lshl_add_u64 v[4:5], v[4:5], 0, s[4:5]
	s_or_b64 s[100:101], vcc, s[100:101]
	s_waitcnt vmcnt(0)
	v_lshlrev_b32_e32 v12, 16, v8
	v_and_b32_e32 v13, 0xffff0000, v8
	v_lshlrev_b32_e32 v14, 16, v9
	v_and_b32_e32 v15, 0xffff0000, v9
	v_lshlrev_b32_e32 v8, 16, v10
	v_and_b32_e32 v9, 0xffff0000, v10
	v_lshlrev_b32_e32 v10, 16, v11
	v_and_b32_e32 v11, 0xffff0000, v11
	global_store_dwordx4 v[6:7], v[12:15], off
	global_store_dwordx4 v[6:7], v[8:11], off offset:16
	v_lshl_add_u64 v[6:7], v[6:7], 0, s[6:7]
	s_andn2_b64 exec, exec, s[100:101]
	s_cbranch_execnz .LBB0_592
.LBB0_593:
	s_or_b64 exec, exec, s[0:1]
	v_mov_b32_e32 v1, v0
	s_nop 1
	s_cmpk_gt_i32 s2, 0x3ff
	v_readfirstlane_b32 s18, v1
	s_cbranch_scc0 .LBB0_669
	s_add_i32 s0, s2, 0xfffffc00
	s_cmp_gt_u32 s0, 43
	s_mov_b64 s[6:7], 0
	s_cbranch_scc1 .LBB0_670
	s_lshl_b32 s0, s0, 7
	s_and_b32 s0, s0, 0x1e00
	s_mov_b32 s1, 0
	s_and_b32 s48, s2, 3
	s_mov_b32 s33, 4
	s_movk_i32 s46, 0x100
	s_mov_b64 s[4:5], -1
	s_andn2_b64 vcc, exec, s[6:7]
	s_cbranch_vccz .LBB0_671
	s_branch .LBB0_676
